# v38 + P2 FFN1-down tile order permuted within each XCD so each round covers 4 row tiles x 8 col tiles (HID read once from HBM instead of twice)
# speedup vs baseline: 1.0050x; 1.0050x over previous
.LBB0_486:
	s_or_b64 exec, exec, s[2:3]
	s_cmpk_lt_i32 s82, 0x200
	s_cselect_b64 s[0:1], -1, 0
	v_mov_b32_e32 v150, v0
	s_waitcnt lgkmcnt(0)
	s_barrier
	v_writelane_b32 v245, s0, 21
	v_readfirstlane_b32 s6, v150
	s_and_b64 vcc, exec, s[0:1]
	v_writelane_b32 v245, s1, 22
	s_cbranch_vccz .LBB0_488
	s_ashr_i32 s0, s82, 31
	s_lshr_b32 s0, s0, 29
	s_add_i32 s0, s82, s0
	s_and_b32 s1, s0, -8
	s_sub_i32 s1, s82, s1
	s_lshl_b32 s3, s1, 6
	s_ashr_i32 s0, s0, 3
	s_mul_i32 s2, s1, 0x41
	s_cmp_lt_i32 s1, 0
	s_cselect_b32 s1, s2, s3
	s_add_i32 s0, s1, s0
	s_and_b32 s98, s0, 3
	s_bfe_u32 s99, s0, 0x10005
	s_lshl_b32 s99, s99, 2
	s_or_b32 s98, s98, s99
	s_bfe_u32 s99, s0, 0x30002
	s_lshl_b32 s99, s99, 3
	s_or_b32 s98, s98, s99
	s_andn2_b32 s0, s0, 63
	s_or_b32 s0, s0, s98
	s_ashr_i32 s1, s0, 31
	s_lshr_b32 s1, s1, 25
	s_add_i32 s1, s0, s1
	s_ashr_i32 s2, s1, 7
	s_and_b32 s1, s1, 0xffffff80
	s_sub_i32 s0, s0, s1
	s_bfe_i32 s1, s0, 0x80000
	s_bfe_u32 s1, s1, 0x3000c
	s_add_i32 s1, s0, s1
	s_bfe_i32 s3, s1, 0x80000
	s_and_b32 s1, s1, 0xf8
	s_sub_i32 s0, s0, s1
	s_lshl_b32 s2, s2, 3
	s_sext_i32_i16 s3, s3
	s_sext_i32_i8 s0, s0
	s_add_i32 s4, s2, s0
	s_ashr_i32 s2, s3, 3

.LBB0_499:
	s_ashr_i32 s5, s5, 3
	s_add_i32 s5, s21, s5
	s_and_b32 s98, s5, 3
	s_bfe_u32 s99, s5, 0x10005
	s_lshl_b32 s99, s99, 2
	s_or_b32 s98, s98, s99
	s_bfe_u32 s99, s5, 0x30002
	s_lshl_b32 s99, s99, 3
	s_or_b32 s98, s98, s99
	s_andn2_b32 s5, s5, 63
	s_or_b32 s5, s5, s98
	s_ashr_i32 s18, s5, 31
	s_lshr_b32 s18, s18, 25
	s_add_i32 s18, s5, s18
	s_ashr_i32 s19, s18, 7
	s_lshl_b32 s19, s19, 3
	s_sub_i32 s20, 32, s19
	s_min_i32 s20, s20, 8
	s_abs_i32 s21, s20
	v_cvt_f32_u32_e32 v2, s21
	s_sub_i32 s23, 0, s21
	s_and_b32 s18, s18, 0xffffff80
	s_sub_i32 s5, s5, s18
	v_rcp_iflag_f32_e32 v2, v2
	s_abs_i32 s18, s5
	s_xor_b32 s22, s5, s20
	s_ashr_i32 s22, s22, 31
	v_mul_f32_e32 v2, 0x4f7ffffe, v2
	v_cvt_u32_f32_e32 v2, v2
	s_nop 0
	v_readfirstlane_b32 s24, v2
	s_mul_i32 s23, s23, s24
	s_mul_hi_u32 s23, s24, s23
	s_add_i32 s24, s24, s23
	s_mul_hi_u32 s23, s18, s24
	s_mul_i32 s24, s23, s21
	s_sub_i32 s18, s18, s24
	s_add_i32 s25, s23, 1
	s_sub_i32 s24, s18, s21
	s_cmp_ge_u32 s18, s21
	s_cselect_b32 s23, s25, s23
	s_cselect_b32 s18, s24, s18
	s_add_i32 s24, s23, 1
	s_cmp_ge_u32 s18, s21
	s_cselect_b32 s18, s24, s23
	s_xor_b32 s18, s18, s22
	s_sub_i32 s18, s18, s22
	s_mul_i32 s20, s18, s20
	s_sub_i32 s5, s5, s20
	s_add_i32 s20, s19, s5
